# MLA loop: idle pad after the last QK MFMA trimmed to the table minimum (8 V-fragment reads + s_nop 3 = 12 wait states)
# speedup vs baseline: 1.0050x; 1.0050x over previous
; #define MFMA(a, b, c) __builtin_amdgcn_mfma_f32_32x32x16_bf16((a), (b), (c), 0, 0, 0)
; DI float xhalf_max(float x) { const auto rr = __builtin_amdgcn_permlane32_swap(__float_as_uint(x), __float_as_uint(x), false, false); return fmaxf(__uint_as_float(rr[0]), __uint_as_float(rr[1])); }
; template <int DQK, int DV, bool BAND> ...
;     ...
;     if constexpr (DQK < 128) {
;       f32x16 p0, p1;
; #pragma unroll
;       for (int r = 0; r < 16; ++r) { p0[r] = 0.f; p1[r] = 0.f; }
;       __builtin_amdgcn_s_setprio(1);
; #pragma unroll
;       for (int d0 = 0; d0 < ND0; ++d0) {
;         const bf16x8 k0f = *(const bf16x8*)&Ks[r32 * KLD + d0 * 16 + hi * 8];
;         const bf16x8 k1f = *(const bf16x8*)&Ks[(32 + r32) * KLD + d0 * 16 + hi * 8];
;         p0 = MFMA(k0f, qf[d0], p0); p1 = MFMA(k1f, qf[d0], p1);
;       }
;       __builtin_amdgcn_s_setprio(0);
;       float mx = fmaxf(p0[0], p1[0]);
; #pragma unroll
;       for (int r = 1; r < 16; ++r) mx = fmaxf(mx, fmaxf(p0[r], p1[r]));
;       mx = xhalf_max(mx);
;       if (__builtin_amdgcn_ballot_w64(mx > m_run + 8.f) != 0ull) {
;         const float m_new = fmaxf(m_run, mx); const float m_use = (m_new == -INFINITY) ? 0.f : m_new;
;         const float alpha = __builtin_amdgcn_exp2f(m_run - m_use);
;         l_run *= alpha; m_run = m_new;
;         if (hi == 0) sc[r32] = alpha;
;         __builtin_amdgcn_fence(__ATOMIC_RELEASE, "wavefront");
;         __builtin_amdgcn_wave_barrier();
; #pragma unroll
;         for (int g4 = 0; g4 < 4; ++g4) { const f32x4 a4 = *(const f32x4*)&sc[8 * g4 + 4 * hi];
; #pragma unroll
;           for (int cb = 0; cb < NCB; ++cb)
; #pragma unroll
;             for (int j = 0; j < 4; ++j) o[cb][4 * g4 + j] *= a4[j]; }
;         __builtin_amdgcn_wave_barrier();
;       }
;       const float m_ref = (m_run == -INFINITY) ? 0.f : m_run;
.LBB1_320:
	ds_read_b128 v[208:211], v132
	ds_read_b128 v[212:215], v132 offset:6656
	ds_read_b128 v[216:219], v132 offset:32
	ds_read_b128 v[220:223], v132 offset:6688
	ds_read_b128 v[224:227], v132 offset:64
	ds_read_b128 v[228:231], v132 offset:6720
	ds_read_b128 v[232:235], v132 offset:96
	ds_read_b128 v[236:239], v132 offset:6752
	ds_read_b128 v[240:243], v132 offset:128
	ds_read_b128 v[244:247], v132 offset:6784
	ds_read_b128 v[248:251], v132 offset:160
	ds_read_b128 v[134:137], v132 offset:6816
	s_waitcnt lgkmcnt(11)
	v_mfma_f32_32x32x16_bf16 v[34:49], v[208:211], v[66:69], v[150:165]
	s_waitcnt lgkmcnt(10)
	v_mfma_f32_32x32x16_bf16 v[50:65], v[212:215], v[66:69], v[150:165]
	s_waitcnt lgkmcnt(9)
	v_mfma_f32_32x32x16_bf16 v[34:49], v[216:219], v[70:73], v[34:49]
	s_waitcnt lgkmcnt(8)
	v_mfma_f32_32x32x16_bf16 v[50:65], v[220:223], v[70:73], v[50:65]
	s_waitcnt lgkmcnt(7)
	v_mfma_f32_32x32x16_bf16 v[34:49], v[224:227], v[74:77], v[34:49]
	s_waitcnt lgkmcnt(6)
	v_mfma_f32_32x32x16_bf16 v[50:65], v[228:231], v[74:77], v[50:65]
	s_waitcnt lgkmcnt(5)
	v_mfma_f32_32x32x16_bf16 v[34:49], v[232:235], v[78:81], v[34:49]
	s_waitcnt lgkmcnt(4)
	v_mfma_f32_32x32x16_bf16 v[50:65], v[236:239], v[78:81], v[50:65]
	s_waitcnt lgkmcnt(3)
	v_mfma_f32_32x32x16_bf16 v[34:49], v[240:243], v[82:85], v[34:49]
	s_waitcnt lgkmcnt(2)
	v_mfma_f32_32x32x16_bf16 v[50:65], v[244:247], v[82:85], v[50:65]
	s_waitcnt lgkmcnt(1)
	v_mfma_f32_32x32x16_bf16 v[34:49], v[248:251], v[86:89], v[34:49]
	s_waitcnt lgkmcnt(0)
	v_mfma_f32_32x32x16_bf16 v[50:65], v[134:137], v[86:89], v[50:65]
	ds_read2_b64 v[208:211], v166 offset0:128 offset1:130
	ds_read2_b64 v[212:215], v167 offset0:160 offset1:162
	ds_read2_b64 v[216:219], v166 offset0:136 offset1:138
	ds_read2_b64 v[220:223], v167 offset0:168 offset1:170
	ds_read2_b64 v[224:227], v166 offset0:132 offset1:134
	ds_read2_b64 v[228:231], v167 offset0:164 offset1:166
	ds_read2_b64 v[232:235], v166 offset0:140 offset1:142
	ds_read2_b64 v[236:239], v167 offset0:172 offset1:174
	s_nop 3
	v_max3_f32 v0, v34, v50, v35
	v_max3_f32 v134, v51, v36, v52
	v_max3_f32 v0, v0, v37, v53
	v_max3_f32 v134, v134, v38, v54
	v_max3_f32 v0, v0, v39, v55
	v_max3_f32 v134, v134, v40, v56
	v_max3_f32 v0, v0, v41, v57
	v_max3_f32 v134, v134, v42, v58
	v_max3_f32 v0, v0, v43, v59
	v_max3_f32 v134, v134, v44, v60
	v_max3_f32 v0, v0, v45, v61
	v_max3_f32 v134, v134, v46, v62
	v_max3_f32 v0, v0, v47, v63
	v_max3_f32 v134, v134, v48, v64
	v_max3_f32 v0, v0, v49, v65
	v_max_f32_e32 v0, v0, v134
	v_mov_b32_e32 v134, v0
	s_nop 1
	v_permlane32_swap_b32_e32 v0, v134
	v_max_f32_e32 v0, v0, v134
	v_sub_f32_e32 v0, v0, v150
	v_add_f32_e32 v134, 0x41000000, v133
	v_cmp_gt_f32_e32 vcc, v0, v134
	s_cbranch_vccz .LBB1_324
	v_max_f32_e32 v0, v0, v0
	v_max_f32_e32 v134, v133, v133
	v_max_f32_e32 v0, v134, v0
	v_cmp_neq_f32_e32 vcc, s7, v0
	s_nop 1
	v_cndmask_b32_e32 v134, 0, v0, vcc
	v_sub_f32_e32 v133, v133, v134
	v_exp_f32_e32 v133, v133
	v_add_f32_e32 v168, v150, v134
	s_and_saveexec_b64 s[22:23], s[36:37]
	ds_write_b32 v124, v133 offset:34816
	s_or_b64 exec, exec, s[22:23]
	s_waitcnt lgkmcnt(0)
	ds_read_b128 v[136:139], v120 offset:34816
	ds_read_b128 v[140:143], v120 offset:34848
	ds_read_b128 v[144:147], v120 offset:34880
	ds_read_b128 v[240:243], v120 offset:34912
	v_mul_f32_e32 v126, v126, v133
	v_sub_f32_e32 v34, v34, v168
	v_sub_f32_e32 v35, v35, v168
	v_sub_f32_e32 v36, v36, v168
	v_sub_f32_e32 v37, v37, v168
	v_sub_f32_e32 v38, v38, v168
	v_sub_f32_e32 v39, v39, v168
	v_sub_f32_e32 v40, v40, v168
	v_sub_f32_e32 v41, v41, v168
	v_sub_f32_e32 v42, v42, v168
	v_sub_f32_e32 v43, v43, v168
	v_sub_f32_e32 v44, v44, v168
	v_sub_f32_e32 v45, v45, v168
	v_sub_f32_e32 v46, v46, v168
	v_sub_f32_e32 v47, v47, v168
	v_sub_f32_e32 v48, v48, v168
	v_sub_f32_e32 v49, v49, v168
	v_sub_f32_e32 v50, v50, v168
	v_sub_f32_e32 v51, v51, v168
	v_sub_f32_e32 v52, v52, v168
	v_sub_f32_e32 v53, v53, v168
	v_sub_f32_e32 v54, v54, v168
	v_sub_f32_e32 v55, v55, v168
	v_sub_f32_e32 v56, v56, v168
	v_sub_f32_e32 v57, v57, v168
	v_sub_f32_e32 v58, v58, v168
	v_sub_f32_e32 v59, v59, v168
	v_sub_f32_e32 v60, v60, v168
	v_sub_f32_e32 v61, v61, v168
	v_sub_f32_e32 v62, v62, v168
	v_sub_f32_e32 v63, v63, v168
	v_sub_f32_e32 v64, v64, v168
	v_sub_f32_e32 v65, v65, v168
	v_sub_f32_e32 v150, 0, v134
	v_mov_b32_e32 v151, v150
	v_mov_b32_e32 v152, v150
	v_mov_b32_e32 v153, v150
	v_mov_b32_e32 v154, v150
	v_mov_b32_e32 v155, v150
	v_mov_b32_e32 v156, v150
	v_mov_b32_e32 v157, v150
	v_mov_b32_e32 v158, v150
	v_mov_b32_e32 v159, v150
	v_mov_b32_e32 v160, v150
	v_mov_b32_e32 v161, v150
	v_mov_b32_e32 v162, v150
	v_mov_b32_e32 v163, v150
	v_mov_b32_e32 v164, v150
	v_mov_b32_e32 v165, v150
	s_waitcnt lgkmcnt(0)
	v_pk_mul_f32 v[2:3], v[2:3], v[136:137]
	v_pk_mul_f32 v[4:5], v[4:5], v[138:139]
	v_pk_mul_f32 v[6:7], v[6:7], v[140:141]
	v_pk_mul_f32 v[8:9], v[8:9], v[142:143]
	v_pk_mul_f32 v[10:11], v[10:11], v[144:145]
	v_pk_mul_f32 v[12:13], v[12:13], v[146:147]
	v_pk_mul_f32 v[14:15], v[14:15], v[240:241]
	v_pk_mul_f32 v[16:17], v[16:17], v[242:243]
	v_pk_mul_f32 v[18:19], v[18:19], v[136:137]
	v_pk_mul_f32 v[20:21], v[20:21], v[138:139]
	v_pk_mul_f32 v[22:23], v[22:23], v[140:141]
	v_pk_mul_f32 v[24:25], v[24:25], v[142:143]
	v_pk_mul_f32 v[26:27], v[26:27], v[144:145]
	v_pk_mul_f32 v[28:29], v[28:29], v[146:147]
	v_pk_mul_f32 v[30:31], v[30:31], v[240:241]
	v_pk_mul_f32 v[32:33], v[32:33], v[242:243]
	s_branch .LBB1_325
